# latent attention unit prologue: K/V tile 0/1 LDS-DMA issued before the waits on the Q loads (one memory latency instead of two per unit)
# baseline (speedup 1.0000x reference)
.LBB0_876:
	s_andn2_b64 vcc, exec, s[2:3]
	s_cbranch_vccnz .LBB0_911
	s_add_i32 s2, s7, 0xffffffb0
	s_lshr_b32 s3, s2, 5
	s_lshl_b32 s28, s2, 3
	s_lshl_b32 s4, s3, 11
	s_lshl_b32 s5, s7, 8
	s_mul_i32 s58, s3, 0x90000
	s_and_b32 s2, s28, 0xc0
	s_lshl_b32 s3, s3, 8
	s_and_b32 s5, s5, 0x700
	v_ashrrev_i32_e32 v1, 6, v212
	v_and_b32_e32 v22, 31, v212
	s_or_b32 s3, s2, s3
	s_mul_i32 s10, s3, 0x900
	v_lshl_or_b32 v2, v1, 5, v22
	s_or_b32 s3, s4, s5
	v_add_u32_e32 v148, s3, v2
	v_ashrrev_i32_e32 v149, 31, v148
	v_readlane_b32 s4, v255, 16
	v_lshlrev_b64 v[2:3], 9, v[148:149]
	v_readlane_b32 s5, v255, 17
	v_bfe_u32 v152, v212, 5, 1
	s_lshl_b32 s2, s2, 1
	v_lshl_add_u64 v[2:3], s[4:5], 0, v[2:3]
	s_mov_b32 s3, s59
	v_lshl_add_u64 v[2:3], v[2:3], 0, s[2:3]
	v_lshlrev_b32_e32 v210, 4, v152
	v_lshl_add_u64 v[14:15], v[2:3], 0, v[210:211]
	global_load_dwordx4 v[2:5], v[14:15], off
	global_load_dwordx4 v[6:9], v[14:15], off offset:32
	global_load_dwordx4 v[10:13], v[14:15], off offset:64
	s_nop 0
	global_load_dwordx4 v[14:17], v[14:15], off offset:96
	s_lshl_b64 s[4:5], s[58:59], 1
	v_readlane_b32 s12, v255, 18
	v_readlane_b32 s13, v255, 19
	s_add_u32 s3, s12, s4
	s_addc_u32 s9, s13, s5
	s_mov_b32 s11, s59
	s_add_u32 s12, s3, s2
	s_addc_u32 s13, s9, 0
	s_lshl_b64 s[10:11], s[10:11], 1
	v_readlane_b32 s14, v255, 20
	v_ashrrev_i32_e32 v142, 3, v212
	v_readlane_b32 s15, v255, 21
	s_add_u32 s10, s14, s10
	v_xor_b32_e32 v144, v223, v212
	v_ashrrev_i32_e32 v143, 31, v142
	v_lshlrev_b32_e32 v157, 4, v212
	s_addc_u32 s11, s15, s11
	v_lshlrev_b64 v[140:141], 9, v[142:143]
	v_readfirstlane_b32 s3, v1
	v_lshlrev_b32_e32 v1, 4, v144
	v_add_u32_e32 v154, 0xc000, v157
	v_mov_b64_e32 v[18:19], s[10:11]
	s_lshl_b32 s3, s3, 10
	s_waitcnt vmcnt(63) expcnt(7) lgkmcnt(15)
	s_barrier
	v_mad_i64_i32 v[18:19], s[10:11], v142, s39, v[18:19]
	s_mov_b32 m0, s3
	v_lshrrev_b32_e32 v23, 5, v212
	v_lshlrev_b32_e32 v159, 7, v22
	s_mov_b32 s22, s8
	s_mov_b32 s23, s8
	s_mov_b32 s9, s8
	s_mov_b32 s10, s8
	s_mov_b32 s11, s8
	s_mov_b32 s14, s8
	s_mov_b32 s15, s8
	s_mov_b32 s16, s8
	s_mov_b32 s17, s8
	s_mov_b32 s18, s8
	s_mov_b32 s19, s8
	s_mov_b32 s20, s8
	s_mov_b32 s21, s8
	v_lshl_add_u64 v[24:25], s[12:13], 0, v[140:141]
	v_and_b32_e32 v26, 0x70, v1
	v_mov_b32_e32 v27, v211
	v_lshl_add_u64 v[20:21], v[24:25], 0, v[26:27]
	v_lshl_add_u64 v[18:19], v[18:19], 0, v[26:27]
	global_load_lds_dwordx4 v[20:21], off
	s_add_i32 m0, s3, 0x2000
	v_lshl_add_u64 v[24:25], v[20:21], 0, s[42:43]
	global_load_lds_dwordx4 v[18:19], off
	s_add_i32 m0, s3, 0x4000
	v_bfe_u32 v1, v212, 1, 3
	global_load_lds_dwordx4 v[24:25], off
	v_lshl_add_u64 v[28:29], v[18:19], 0, s[66:67]
	s_add_i32 m0, s3, 0x6000
	s_mov_b32 s12, s8
	global_load_lds_dwordx4 v[28:29], off
	s_waitcnt vmcnt(7)
	ds_write_b128 v157, v[2:5] offset:49152
	s_waitcnt vmcnt(6)
	ds_write_b128 v157, v[6:9] offset:57344
	s_waitcnt vmcnt(5)
	ds_write_b128 v154, v[10:13] offset:16384
	s_waitcnt vmcnt(4)
	ds_write_b128 v154, v[14:17] offset:24576
	v_bitop3_b32 v2, v23, v1, 1 bitop3:0x6c
	v_lshlrev_b32_e32 v158, 4, v2
	v_or_b32_e32 v30, v159, v158
	s_waitcnt vmcnt(0)
	s_waitcnt vmcnt(0) lgkmcnt(0)
	s_barrier
	ds_read_b128 v[22:25], v30
	ds_read_b128 v[26:29], v157 offset:49152
	s_mov_b32 s13, s8
	v_mov_b64_e32 v[110:111], s[22:23]
	v_mov_b64_e32 v[108:109], s[20:21]
	v_mov_b64_e32 v[106:107], s[18:19]
	v_mov_b64_e32 v[104:105], s[16:17]
	v_mov_b64_e32 v[102:103], s[14:15]
	v_mov_b64_e32 v[100:101], s[12:13]
	v_mov_b64_e32 v[98:99], s[10:11]
	v_mov_b64_e32 v[96:97], s[8:9]
	s_mov_b64 s[10:11], 0x10000
	v_lshl_add_u64 v[20:21], v[20:21], 0, s[10:11]
	s_waitcnt lgkmcnt(0)
	v_mfma_f32_32x32x16_f16 v[2:17], v[22:25], v[26:29], v[96:111]
	v_bitop3_b32 v22, v152, v1, 2 bitop3:0x36
	v_lshlrev_b32_e32 v160, 4, v22
	v_or_b32_e32 v31, v159, v160
	ds_read_b128 v[22:25], v31
	ds_read_b128 v[26:29], v157 offset:57344
	s_add_i32 m0, s3, 0x8000
	v_lshl_add_u64 v[18:19], v[18:19], 0, s[76:77]
	s_waitcnt lgkmcnt(0)
	v_mfma_f32_32x32x16_f16 v[2:17], v[22:25], v[26:29], v[2:17]
	v_bitop3_b32 v22, v152, v1, 4 bitop3:0x36
	v_lshlrev_b32_e32 v156, 4, v22
	v_or_b32_e32 v22, v159, v156
	ds_read_b128 v[22:25], v22
	ds_read_b128 v[26:29], v154 offset:16384
	v_bitop3_b32 v1, v152, v1, 6 bitop3:0x36
	v_lshlrev_b32_e32 v155, 4, v1
	v_or_b32_e32 v1, v159, v155
	s_waitcnt lgkmcnt(0)
	v_mfma_f32_32x32x16_f16 v[48:63], v[22:25], v[26:29], v[96:111]
	ds_read_b128 v[22:25], v1
	ds_read_b128 v[26:29], v154 offset:24576
	global_load_lds_dwordx4 v[20:21], off
	s_add_i32 m0, s3, 0xa000
	v_xor_b32_e32 v1, 32, v215
	global_load_lds_dwordx4 v[18:19], off
	ds_read_b128 v[18:21], v30 offset:4096
	ds_read_b128 v[136:139], v157 offset:49152
	s_waitcnt lgkmcnt(0)
	v_mfma_f32_32x32x16_f16 v[96:111], v[18:21], v[136:139], v[96:111]
	ds_read_b128 v[18:21], v31 offset:4096
	ds_read_b128 v[132:135], v157 offset:57344
	s_cmp_eq_u64 exec, 0
	v_mfma_f32_32x32x16_f16 v[48:63], v[22:25], v[26:29], v[48:63]
	v_and_b32_e32 v22, 64, v215
	v_add_u32_e32 v22, 64, v22
	v_cmp_lt_i32_e32 vcc, v1, v22
	s_nop 1
	v_cndmask_b32_e32 v1, v215, v1, vcc
	v_lshlrev_b32_e32 v153, 2, v1
	s_waitcnt lgkmcnt(0)
	v_mfma_f32_32x32x16_f16 v[96:111], v[18:21], v[132:135], v[96:111]
	v_max_f32_e32 v1, v3, v3
	v_max_f32_e32 v18, v2, v2
	v_max_f32_e32 v1, v18, v1
	v_max3_f32 v1, v1, v4, v5
	v_max3_f32 v1, v1, v6, v7
	v_max3_f32 v1, v1, v8, v9
	v_max3_f32 v1, v1, v10, v11
	v_max3_f32 v1, v1, v12, v13
	v_max3_f32 v1, v1, v14, v15
	v_max3_f32 v1, v1, v16, v17
	ds_bpermute_b32 v18, v153, v1
	s_cbranch_scc1 .LBB0_879
	s_waitcnt lgkmcnt(0)
	v_max_f32_e32 v18, v18, v18
	v_max_f32_e32 v1, v1, v1
	v_max_f32_e32 v18, v1, v18
	v_add_f32_e32 v169, 0, v18
	v_pk_add_f32 v[2:3], v[2:3], v[18:19] op_sel_hi:[1,0] neg_lo:[0,1] neg_hi:[0,1]
	v_pk_add_f32 v[4:5], v[4:5], v[18:19] op_sel_hi:[1,0] neg_lo:[0,1] neg_hi:[0,1]
	v_pk_add_f32 v[6:7], v[6:7], v[18:19] op_sel_hi:[1,0] neg_lo:[0,1] neg_hi:[0,1]
	v_pk_add_f32 v[8:9], v[8:9], v[18:19] op_sel_hi:[1,0] neg_lo:[0,1] neg_hi:[0,1]
	v_pk_add_f32 v[10:11], v[10:11], v[18:19] op_sel_hi:[1,0] neg_lo:[0,1] neg_hi:[0,1]
	v_pk_add_f32 v[12:13], v[12:13], v[18:19] op_sel_hi:[1,0] neg_lo:[0,1] neg_hi:[0,1]
	v_pk_add_f32 v[14:15], v[14:15], v[18:19] op_sel_hi:[1,0] neg_lo:[0,1] neg_hi:[0,1]
	v_pk_add_f32 v[16:17], v[16:17], v[18:19] op_sel_hi:[1,0] neg_lo:[0,1] neg_hi:[0,1]
	v_sub_f32_e32 v111, v111, v18
	v_sub_f32_e32 v110, v110, v18
	v_sub_f32_e32 v109, v109, v18
	v_sub_f32_e32 v108, v108, v18
	v_sub_f32_e32 v107, v107, v18
	v_sub_f32_e32 v106, v106, v18
	v_sub_f32_e32 v105, v105, v18
	v_sub_f32_e32 v104, v104, v18
	v_sub_f32_e32 v103, v103, v18
	v_sub_f32_e32 v102, v102, v18
	v_sub_f32_e32 v101, v101, v18
	v_sub_f32_e32 v100, v100, v18
	v_sub_f32_e32 v99, v99, v18
	v_sub_f32_e32 v98, v98, v18
	v_sub_f32_e32 v97, v97, v18
	v_sub_f32_e32 v96, v96, v18
	s_branch .LBB0_880
